# v31 + prep section reorder for half the workgroups + dead denormal guard removed from FFN-up epilogue rsqrt chains
# speedup vs baseline: 1.0102x; 1.0051x over previous
; __device__ __forceinline__ unsigned pk2(float lo, float hi) { const f32v2_t v = {lo, hi}; const bf16v2_t b = __builtin_convertvector(v, bf16v2_t); return __builtin_bit_cast(unsigned, b); }
; #define ST_OUT(p, v) __builtin_nontemporal_store((v), (p))
;     __device__ __forceinline__ void operator()(AccRef acc, const Unit& u, int wr, int wc, int fr, int fq) const {
;         const int row0 = u.pm * BM + wr * 64 + fr, col0 = u.pn * 128 + wc * 32 + 8 * fq;
; #pragma unroll
;         for (int ai = 0; ai < 2; ++ai)
; #pragma unroll
;             for (int m = 0; m < 4; ++m) {
;                 const int row = row0 + ai * HALF + m * 16;
;                 const float rinv = rsqrtf((float)rss[row] * (1.f / (16777216.f * DM)) + EPS);
;                 const float nrl = rinv * -1.4426950408889634f, r2 = rinv * rinv;
;                 unsigned ow[4];
; #pragma unroll
;                 for (int n = 0; n < 2; ++n)
; #pragma unroll
;                     for (int jp = 0; jp < 2; ++jp) {
;                         const f32v2_t ag = {acc[ai][0][m][n][2 * jp], acc[ai][0][m][n][2 * jp + 1]}, au = {acc[ai][1][m][n][2 * jp], acc[ai][1][m][n][2 * jp + 1]};
;                         const f32v2_t t = ag * nrl;
;                         f32v2_t e; e.x = __builtin_amdgcn_exp2f(t.x); e.y = __builtin_amdgcn_exp2f(t.y);
;                         const f32v2_t d = e + 1.0f;
;                         f32v2_t r; r.x = __builtin_amdgcn_rcpf(d.x); r.y = __builtin_amdgcn_rcpf(d.y);
;                         const f32v2_t hv = (ag * au) * (r * r2);
;                         ow[n * 2 + jp] = pk2(hv.x, hv.y);
;                     }
;                 u32x4 o; o.x = ow[0]; o.y = ow[1]; o.z = ow[2]; o.w = ow[3];
;                 ST_OUT((u32x4*)(H + (size_t)row * FF + col0), o);
.LBB0_748:
	v_lshl_add_u32 v156, s27, 8, v162
	v_ashrrev_i32_e32 v157, 31, v156
	v_lshl_add_u64 v[158:159], v[156:157], 3, s[40:41]
	global_load_dwordx2 v[182:183], v[158:159], off
	global_load_dwordx2 v[184:185], v[158:159], off offset:128
	global_load_dwordx2 v[186:187], v[158:159], off offset:256
	global_load_dwordx2 v[188:189], v[158:159], off offset:384
	global_load_dwordx2 v[194:195], v[158:159], off offset:1024
	global_load_dwordx2 v[196:197], v[158:159], off offset:1152
	global_load_dwordx2 v[198:199], v[158:159], off offset:1280
	global_load_dwordx2 v[200:201], v[158:159], off offset:1408
	v_pk_mul_f32 v[120:121], v[124:125], v[120:121]
	v_pk_mul_f32 v[122:123], v[126:127], v[122:123]
	v_pk_mul_f32 v[112:113], v[116:117], v[112:113]
	v_pk_mul_f32 v[114:115], v[118:119], v[114:115]
	v_pk_mul_f32 v[104:105], v[108:109], v[104:105]
	v_pk_mul_f32 v[106:107], v[110:111], v[106:107]
	v_pk_mul_f32 v[96:97], v[100:101], v[96:97]
	v_pk_mul_f32 v[98:99], v[102:103], v[98:99]
	v_pk_mul_f32 v[88:89], v[92:93], v[88:89]
	v_pk_mul_f32 v[90:91], v[94:95], v[90:91]
	v_pk_mul_f32 v[80:81], v[84:85], v[80:81]
	v_pk_mul_f32 v[82:83], v[86:87], v[82:83]
	v_pk_mul_f32 v[72:73], v[76:77], v[72:73]
	v_pk_mul_f32 v[74:75], v[78:79], v[74:75]
	v_pk_mul_f32 v[64:65], v[68:69], v[64:65]
	v_pk_mul_f32 v[66:67], v[70:71], v[66:67]
	v_pk_mul_f32 v[56:57], v[60:61], v[56:57]
	v_pk_mul_f32 v[58:59], v[62:63], v[58:59]
	v_pk_mul_f32 v[48:49], v[52:53], v[48:49]
	v_pk_mul_f32 v[50:51], v[54:55], v[50:51]
	v_pk_mul_f32 v[40:41], v[44:45], v[40:41]
	v_pk_mul_f32 v[42:43], v[46:47], v[42:43]
	v_pk_mul_f32 v[32:33], v[36:37], v[32:33]
	v_pk_mul_f32 v[34:35], v[38:39], v[34:35]
	v_pk_mul_f32 v[24:25], v[28:29], v[24:25]
	v_pk_mul_f32 v[26:27], v[30:31], v[26:27]
	v_pk_mul_f32 v[16:17], v[20:21], v[16:17]
	v_pk_mul_f32 v[18:19], v[22:23], v[18:19]
	v_pk_mul_f32 v[8:9], v[12:13], v[8:9]
	v_pk_mul_f32 v[10:11], v[14:15], v[10:11]
	v_pk_mul_f32 v[0:1], v[4:5], v[0:1]
	v_pk_mul_f32 v[2:3], v[6:7], v[2:3]
	v_readlane_b32 s16, v253, 42
	v_lshl_or_b32 v160, s20, 7, v164
	v_readlane_b32 s17, v253, 43
	v_ashrrev_i32_e32 v161, 31, v160
	v_lshlrev_b64 v[204:205], 1, v[160:161]
	s_mov_b32 s101, 0
	v_mov_b64_e32 v[202:203], s[16:17]
	v_mad_i64_i32 v[202:203], s[22:23], v156, s6, v[202:203]
	v_lshl_add_u64 v[202:203], v[202:203], 0, v[204:205]
	s_waitcnt vmcnt(0)
	v_ffbh_u32_e32 v166, v183
	v_ffbh_u32_e32 v167, v185
	v_ffbh_u32_e32 v168, v187
	v_ffbh_u32_e32 v169, v189
	v_ffbh_u32_e32 v170, v195
	v_ffbh_u32_e32 v171, v197
	v_ffbh_u32_e32 v172, v199
	v_ffbh_u32_e32 v173, v201
	v_min_u32_e32 v166, 32, v166
	v_min_u32_e32 v167, 32, v167
	v_min_u32_e32 v168, 32, v168
	v_min_u32_e32 v169, 32, v169
	v_min_u32_e32 v170, 32, v170
	v_min_u32_e32 v171, 32, v171
	v_min_u32_e32 v172, 32, v172
	v_min_u32_e32 v173, 32, v173
	v_lshlrev_b64 v[182:183], v166, v[182:183]
	v_lshlrev_b64 v[184:185], v167, v[184:185]
	v_lshlrev_b64 v[186:187], v168, v[186:187]
	v_lshlrev_b64 v[188:189], v169, v[188:189]
	v_lshlrev_b64 v[194:195], v170, v[194:195]
	v_lshlrev_b64 v[196:197], v171, v[196:197]
	v_lshlrev_b64 v[198:199], v172, v[198:199]
	v_lshlrev_b64 v[200:201], v173, v[200:201]
	v_min_u32_e32 v182, 1, v182
	v_min_u32_e32 v184, 1, v184
	v_min_u32_e32 v186, 1, v186
	v_min_u32_e32 v188, 1, v188
	v_min_u32_e32 v194, 1, v194
	v_min_u32_e32 v196, 1, v196
	v_min_u32_e32 v198, 1, v198
	v_min_u32_e32 v200, 1, v200
	v_or_b32_e32 v182, v183, v182
	v_or_b32_e32 v184, v185, v184
	v_or_b32_e32 v186, v187, v186
	v_or_b32_e32 v188, v189, v188
	v_or_b32_e32 v194, v195, v194
	v_or_b32_e32 v196, v197, v196
	v_or_b32_e32 v198, v199, v198
	v_or_b32_e32 v200, v201, v200
	v_cvt_f32_u32_e32 v182, v182
	v_cvt_f32_u32_e32 v184, v184
	v_cvt_f32_u32_e32 v186, v186
	v_cvt_f32_u32_e32 v188, v188
	v_cvt_f32_u32_e32 v194, v194
	v_cvt_f32_u32_e32 v196, v196
	v_cvt_f32_u32_e32 v198, v198
	v_cvt_f32_u32_e32 v200, v200
	v_sub_u32_e32 v166, 32, v166
	v_sub_u32_e32 v167, 32, v167
	v_sub_u32_e32 v168, 32, v168
	v_sub_u32_e32 v169, 32, v169
	v_sub_u32_e32 v170, 32, v170
	v_sub_u32_e32 v171, 32, v171
	v_sub_u32_e32 v172, 32, v172
	v_sub_u32_e32 v173, 32, v173
	v_ldexp_f32 v166, v182, v166
	v_ldexp_f32 v167, v184, v167
	v_ldexp_f32 v168, v186, v168
	v_ldexp_f32 v169, v188, v169
	v_ldexp_f32 v170, v194, v170
	v_ldexp_f32 v171, v196, v171
	v_ldexp_f32 v172, v198, v172
	v_ldexp_f32 v173, v200, v173
	v_fmamk_f32 v166, v166, 0x2e000000, v176
	v_fmamk_f32 v167, v167, 0x2e000000, v176
	v_fmamk_f32 v168, v168, 0x2e000000, v176
	v_fmamk_f32 v169, v169, 0x2e000000, v176
	v_fmamk_f32 v170, v170, 0x2e000000, v176
	v_fmamk_f32 v171, v171, 0x2e000000, v176
	v_fmamk_f32 v172, v172, 0x2e000000, v176
	v_fmamk_f32 v173, v173, 0x2e000000, v176
	v_rsq_f32_e32 v166, v166
	v_rsq_f32_e32 v167, v167
	v_rsq_f32_e32 v168, v168
	v_rsq_f32_e32 v169, v169
	v_rsq_f32_e32 v170, v170
	v_rsq_f32_e32 v171, v171
	v_rsq_f32_e32 v172, v172
	v_rsq_f32_e32 v173, v173
	v_mul_f32_e32 v206, 0xbfb8aa3b, v166
	v_mul_f32_e32 v210, 0xbfb8aa3b, v167
	v_mul_f32_e32 v214, 0xbfb8aa3b, v168
	v_mul_f32_e32 v218, 0xbfb8aa3b, v169
	v_mul_f32_e32 v222, 0xbfb8aa3b, v170
	v_mul_f32_e32 v226, 0xbfb8aa3b, v171
	v_mul_f32_e32 v230, 0xbfb8aa3b, v172
	v_mul_f32_e32 v234, 0xbfb8aa3b, v173
	v_mul_f32_e32 v208, v166, v166
	v_mul_f32_e32 v212, v167, v167
	v_mul_f32_e32 v216, v168, v168
	v_mul_f32_e32 v220, v169, v169
	v_mul_f32_e32 v224, v170, v170
	v_mul_f32_e32 v228, v171, v171
	v_mul_f32_e32 v232, v172, v172
	v_mul_f32_e32 v236, v173, v173
	v_pk_mul_f32 v[124:125], v[124:125], v[206:207] op_sel_hi:[1,0]
	v_pk_mul_f32 v[126:127], v[126:127], v[206:207] op_sel_hi:[1,0]
	v_pk_mul_f32 v[116:117], v[116:117], v[206:207] op_sel_hi:[1,0]
; __device__ __forceinline__ unsigned pk2(float lo, float hi) { const f32v2_t v = {lo, hi}; const bf16v2_t b = __builtin_convertvector(v, bf16v2_t); return __builtin_bit_cast(unsigned, b); }
; #define ST_OUT(p, v) __builtin_nontemporal_store((v), (p))
;     __device__ __forceinline__ void operator()(AccRef acc, const Unit& u, int wr, int wc, int fr, int fq) const {
;     ...
;                 for (int n = 0; n < 2; ++n)
; #pragma unroll
;                     for (int jp = 0; jp < 2; ++jp) {
;                         const f32v2_t ag = {acc[ai][0][m][n][2 * jp], acc[ai][0][m][n][2 * jp + 1]}, au = {acc[ai][1][m][n][2 * jp], acc[ai][1][m][n][2 * jp + 1]};
;                         const f32v2_t t = ag * nrl;
;                         f32v2_t e; e.x = __builtin_amdgcn_exp2f(t.x); e.y = __builtin_amdgcn_exp2f(t.y);
;                         const f32v2_t d = e + 1.0f;
;                         f32v2_t r; r.x = __builtin_amdgcn_rcpf(d.x); r.y = __builtin_amdgcn_rcpf(d.y);
;                         const f32v2_t hv = (ag * au) * (r * r2);
;                         ow[n * 2 + jp] = pk2(hv.x, hv.y);
;                     }
;                 u32x4 o; o.x = ow[0]; o.y = ow[1]; o.z = ow[2]; o.w = ow[3];
;                 ST_OUT((u32x4*)(H + (size_t)row * FF + col0), o);
	v_pk_mul_f32 v[118:119], v[118:119], v[206:207] op_sel_hi:[1,0]
	v_exp_f32_e32 v124, v124
	v_exp_f32_e32 v125, v125
	v_exp_f32_e32 v126, v126
	v_exp_f32_e32 v127, v127
	v_exp_f32_e32 v116, v116
	v_exp_f32_e32 v117, v117
	v_exp_f32_e32 v118, v118
	v_exp_f32_e32 v119, v119
	s_mov_b32 s100, 0x0
	v_pk_add_f32 v[124:125], v[124:125], 1.0 op_sel_hi:[1,0]
	v_pk_add_f32 v[126:127], v[126:127], 1.0 op_sel_hi:[1,0]
	v_pk_add_f32 v[116:117], v[116:117], 1.0 op_sel_hi:[1,0]
	v_pk_add_f32 v[118:119], v[118:119], 1.0 op_sel_hi:[1,0]
	v_rcp_f32_e32 v124, v124
	v_rcp_f32_e32 v125, v125
	v_rcp_f32_e32 v126, v126
	v_rcp_f32_e32 v127, v127
	v_rcp_f32_e32 v116, v116
	v_rcp_f32_e32 v117, v117
	v_rcp_f32_e32 v118, v118
	v_rcp_f32_e32 v119, v119
	v_lshl_add_u64 v[204:205], v[202:203], 0, s[100:101]
	v_pk_mul_f32 v[124:125], v[208:209], v[124:125] op_sel_hi:[0,1]
	v_pk_mul_f32 v[126:127], v[208:209], v[126:127] op_sel_hi:[0,1]
	v_pk_mul_f32 v[116:117], v[208:209], v[116:117] op_sel_hi:[0,1]
	v_pk_mul_f32 v[118:119], v[208:209], v[118:119] op_sel_hi:[0,1]
	v_pk_mul_f32 v[120:121], v[120:121], v[124:125]
	v_pk_mul_f32 v[122:123], v[122:123], v[126:127]
	v_pk_mul_f32 v[112:113], v[112:113], v[116:117]
	v_pk_mul_f32 v[114:115], v[114:115], v[118:119]
	v_cvt_pk_bf16_f32 v124, v120, v121
	v_cvt_pk_bf16_f32 v125, v122, v123
	v_cvt_pk_bf16_f32 v126, v112, v113
	v_cvt_pk_bf16_f32 v127, v114, v115
	global_store_dwordx4 v[204:205], v[124:127], off nt
	v_pk_mul_f32 v[108:109], v[108:109], v[210:211] op_sel_hi:[1,0]
	v_pk_mul_f32 v[110:111], v[110:111], v[210:211] op_sel_hi:[1,0]
	v_pk_mul_f32 v[100:101], v[100:101], v[210:211] op_sel_hi:[1,0]
	v_pk_mul_f32 v[102:103], v[102:103], v[210:211] op_sel_hi:[1,0]
	v_exp_f32_e32 v108, v108
	v_exp_f32_e32 v109, v109
	v_exp_f32_e32 v110, v110
	v_exp_f32_e32 v111, v111
	v_exp_f32_e32 v100, v100
	v_exp_f32_e32 v101, v101
	v_exp_f32_e32 v102, v102
	v_exp_f32_e32 v103, v103
	s_mov_b32 s100, 0x2c000
	v_pk_add_f32 v[108:109], v[108:109], 1.0 op_sel_hi:[1,0]
	v_pk_add_f32 v[110:111], v[110:111], 1.0 op_sel_hi:[1,0]
	v_pk_add_f32 v[100:101], v[100:101], 1.0 op_sel_hi:[1,0]
	v_pk_add_f32 v[102:103], v[102:103], 1.0 op_sel_hi:[1,0]
	v_rcp_f32_e32 v108, v108
	v_rcp_f32_e32 v109, v109
	v_rcp_f32_e32 v110, v110
	v_rcp_f32_e32 v111, v111
	v_rcp_f32_e32 v100, v100
	v_rcp_f32_e32 v101, v101
	v_rcp_f32_e32 v102, v102
	v_rcp_f32_e32 v103, v103
	v_lshl_add_u64 v[204:205], v[202:203], 0, s[100:101]
	v_pk_mul_f32 v[108:109], v[212:213], v[108:109] op_sel_hi:[0,1]
	v_pk_mul_f32 v[110:111], v[212:213], v[110:111] op_sel_hi:[0,1]
	v_pk_mul_f32 v[100:101], v[212:213], v[100:101] op_sel_hi:[0,1]
	v_pk_mul_f32 v[102:103], v[212:213], v[102:103] op_sel_hi:[0,1]
	v_pk_mul_f32 v[104:105], v[104:105], v[108:109]
	v_pk_mul_f32 v[106:107], v[106:107], v[110:111]
	v_pk_mul_f32 v[96:97], v[96:97], v[100:101]
	v_pk_mul_f32 v[98:99], v[98:99], v[102:103]
	v_cvt_pk_bf16_f32 v108, v104, v105
	v_cvt_pk_bf16_f32 v109, v106, v107
	v_cvt_pk_bf16_f32 v110, v96, v97
	v_cvt_pk_bf16_f32 v111, v98, v99
	global_store_dwordx4 v[204:205], v[108:111], off nt
	v_pk_mul_f32 v[92:93], v[92:93], v[214:215] op_sel_hi:[1,0]
	v_pk_mul_f32 v[94:95], v[94:95], v[214:215] op_sel_hi:[1,0]
	v_pk_mul_f32 v[84:85], v[84:85], v[214:215] op_sel_hi:[1,0]
	v_pk_mul_f32 v[86:87], v[86:87], v[214:215] op_sel_hi:[1,0]
	v_exp_f32_e32 v92, v92
	v_exp_f32_e32 v93, v93
	v_exp_f32_e32 v94, v94
	v_exp_f32_e32 v95, v95
	v_exp_f32_e32 v84, v84
	v_exp_f32_e32 v85, v85
	v_exp_f32_e32 v86, v86
	v_exp_f32_e32 v87, v87
	s_mov_b32 s100, 0x58000
	v_pk_add_f32 v[92:93], v[92:93], 1.0 op_sel_hi:[1,0]
	v_pk_add_f32 v[94:95], v[94:95], 1.0 op_sel_hi:[1,0]
	v_pk_add_f32 v[84:85], v[84:85], 1.0 op_sel_hi:[1,0]
	v_pk_add_f32 v[86:87], v[86:87], 1.0 op_sel_hi:[1,0]
	v_rcp_f32_e32 v92, v92
	v_rcp_f32_e32 v93, v93
	v_rcp_f32_e32 v94, v94
	v_rcp_f32_e32 v95, v95
	v_rcp_f32_e32 v84, v84
	v_rcp_f32_e32 v85, v85
	v_rcp_f32_e32 v86, v86
	v_rcp_f32_e32 v87, v87
	v_lshl_add_u64 v[204:205], v[202:203], 0, s[100:101]
	v_pk_mul_f32 v[92:93], v[216:217], v[92:93] op_sel_hi:[0,1]
	v_pk_mul_f32 v[94:95], v[216:217], v[94:95] op_sel_hi:[0,1]
	v_pk_mul_f32 v[84:85], v[216:217], v[84:85] op_sel_hi:[0,1]
	v_pk_mul_f32 v[86:87], v[216:217], v[86:87] op_sel_hi:[0,1]
	v_pk_mul_f32 v[88:89], v[88:89], v[92:93]
	v_pk_mul_f32 v[90:91], v[90:91], v[94:95]
	v_pk_mul_f32 v[80:81], v[80:81], v[84:85]
	v_pk_mul_f32 v[82:83], v[82:83], v[86:87]
	v_cvt_pk_bf16_f32 v92, v88, v89
	v_cvt_pk_bf16_f32 v93, v90, v91
	v_cvt_pk_bf16_f32 v94, v80, v81
	v_cvt_pk_bf16_f32 v95, v82, v83
	global_store_dwordx4 v[204:205], v[92:95], off nt
	v_pk_mul_f32 v[76:77], v[76:77], v[218:219] op_sel_hi:[1,0]
	v_pk_mul_f32 v[78:79], v[78:79], v[218:219] op_sel_hi:[1,0]
	v_pk_mul_f32 v[68:69], v[68:69], v[218:219] op_sel_hi:[1,0]
	v_pk_mul_f32 v[70:71], v[70:71], v[218:219] op_sel_hi:[1,0]
	v_exp_f32_e32 v76, v76
	v_exp_f32_e32 v77, v77
	v_exp_f32_e32 v78, v78
	v_exp_f32_e32 v79, v79
	v_exp_f32_e32 v68, v68
	v_exp_f32_e32 v69, v69
	v_exp_f32_e32 v70, v70
	v_exp_f32_e32 v71, v71
	s_mov_b32 s100, 0x84000
	v_pk_add_f32 v[76:77], v[76:77], 1.0 op_sel_hi:[1,0]
	v_pk_add_f32 v[78:79], v[78:79], 1.0 op_sel_hi:[1,0]
	v_pk_add_f32 v[68:69], v[68:69], 1.0 op_sel_hi:[1,0]
	v_pk_add_f32 v[70:71], v[70:71], 1.0 op_sel_hi:[1,0]
	v_rcp_f32_e32 v76, v76
	v_rcp_f32_e32 v77, v77
	v_rcp_f32_e32 v78, v78
	v_rcp_f32_e32 v79, v79
	v_rcp_f32_e32 v68, v68
	v_rcp_f32_e32 v69, v69
	v_rcp_f32_e32 v70, v70
	v_rcp_f32_e32 v71, v71
	v_lshl_add_u64 v[204:205], v[202:203], 0, s[100:101]
	v_pk_mul_f32 v[76:77], v[220:221], v[76:77] op_sel_hi:[0,1]
	v_pk_mul_f32 v[78:79], v[220:221], v[78:79] op_sel_hi:[0,1]
; __device__ __forceinline__ unsigned pk2(float lo, float hi) { const f32v2_t v = {lo, hi}; const bf16v2_t b = __builtin_convertvector(v, bf16v2_t); return __builtin_bit_cast(unsigned, b); }
; #define ST_OUT(p, v) __builtin_nontemporal_store((v), (p))
;     __device__ __forceinline__ void operator()(AccRef acc, const Unit& u, int wr, int wc, int fr, int fq) const {
;     ...
;                 for (int n = 0; n < 2; ++n)
; #pragma unroll
;                     for (int jp = 0; jp < 2; ++jp) {
;                         const f32v2_t ag = {acc[ai][0][m][n][2 * jp], acc[ai][0][m][n][2 * jp + 1]}, au = {acc[ai][1][m][n][2 * jp], acc[ai][1][m][n][2 * jp + 1]};
;                         const f32v2_t t = ag * nrl;
;                         f32v2_t e; e.x = __builtin_amdgcn_exp2f(t.x); e.y = __builtin_amdgcn_exp2f(t.y);
;                         const f32v2_t d = e + 1.0f;
;                         f32v2_t r; r.x = __builtin_amdgcn_rcpf(d.x); r.y = __builtin_amdgcn_rcpf(d.y);
;                         const f32v2_t hv = (ag * au) * (r * r2);
;                         ow[n * 2 + jp] = pk2(hv.x, hv.y);
;                     }
;                 u32x4 o; o.x = ow[0]; o.y = ow[1]; o.z = ow[2]; o.w = ow[3];
;                 ST_OUT((u32x4*)(H + (size_t)row * FF + col0), o);
	v_pk_mul_f32 v[68:69], v[220:221], v[68:69] op_sel_hi:[0,1]
	v_pk_mul_f32 v[70:71], v[220:221], v[70:71] op_sel_hi:[0,1]
	v_pk_mul_f32 v[72:73], v[72:73], v[76:77]
	v_pk_mul_f32 v[74:75], v[74:75], v[78:79]
	v_pk_mul_f32 v[64:65], v[64:65], v[68:69]
	v_pk_mul_f32 v[66:67], v[66:67], v[70:71]
	v_cvt_pk_bf16_f32 v76, v72, v73
	v_cvt_pk_bf16_f32 v77, v74, v75
	v_cvt_pk_bf16_f32 v78, v64, v65
	v_cvt_pk_bf16_f32 v79, v66, v67
	global_store_dwordx4 v[204:205], v[76:79], off nt
	v_pk_mul_f32 v[60:61], v[60:61], v[222:223] op_sel_hi:[1,0]
	v_pk_mul_f32 v[62:63], v[62:63], v[222:223] op_sel_hi:[1,0]
	v_pk_mul_f32 v[52:53], v[52:53], v[222:223] op_sel_hi:[1,0]
	v_pk_mul_f32 v[54:55], v[54:55], v[222:223] op_sel_hi:[1,0]
	v_exp_f32_e32 v60, v60
	v_exp_f32_e32 v61, v61
	v_exp_f32_e32 v62, v62
	v_exp_f32_e32 v63, v63
	v_exp_f32_e32 v52, v52
	v_exp_f32_e32 v53, v53
	v_exp_f32_e32 v54, v54
	v_exp_f32_e32 v55, v55
	s_mov_b32 s100, 0x160000
	v_pk_add_f32 v[60:61], v[60:61], 1.0 op_sel_hi:[1,0]
	v_pk_add_f32 v[62:63], v[62:63], 1.0 op_sel_hi:[1,0]
	v_pk_add_f32 v[52:53], v[52:53], 1.0 op_sel_hi:[1,0]
	v_pk_add_f32 v[54:55], v[54:55], 1.0 op_sel_hi:[1,0]
	v_rcp_f32_e32 v60, v60
	v_rcp_f32_e32 v61, v61
	v_rcp_f32_e32 v62, v62
	v_rcp_f32_e32 v63, v63
	v_rcp_f32_e32 v52, v52
	v_rcp_f32_e32 v53, v53
	v_rcp_f32_e32 v54, v54
	v_rcp_f32_e32 v55, v55
	v_lshl_add_u64 v[204:205], v[202:203], 0, s[100:101]
	v_pk_mul_f32 v[60:61], v[224:225], v[60:61] op_sel_hi:[0,1]
	v_pk_mul_f32 v[62:63], v[224:225], v[62:63] op_sel_hi:[0,1]
	v_pk_mul_f32 v[52:53], v[224:225], v[52:53] op_sel_hi:[0,1]
	v_pk_mul_f32 v[54:55], v[224:225], v[54:55] op_sel_hi:[0,1]
	v_pk_mul_f32 v[56:57], v[56:57], v[60:61]
	v_pk_mul_f32 v[58:59], v[58:59], v[62:63]
	v_pk_mul_f32 v[48:49], v[48:49], v[52:53]
	v_pk_mul_f32 v[50:51], v[50:51], v[54:55]
	v_cvt_pk_bf16_f32 v60, v56, v57
	v_cvt_pk_bf16_f32 v61, v58, v59
	v_cvt_pk_bf16_f32 v62, v48, v49
	v_cvt_pk_bf16_f32 v63, v50, v51
	global_store_dwordx4 v[204:205], v[60:63], off nt
	v_pk_mul_f32 v[44:45], v[44:45], v[226:227] op_sel_hi:[1,0]
	v_pk_mul_f32 v[46:47], v[46:47], v[226:227] op_sel_hi:[1,0]
	v_pk_mul_f32 v[36:37], v[36:37], v[226:227] op_sel_hi:[1,0]
	v_pk_mul_f32 v[38:39], v[38:39], v[226:227] op_sel_hi:[1,0]
	v_exp_f32_e32 v44, v44
	v_exp_f32_e32 v45, v45
	v_exp_f32_e32 v46, v46
	v_exp_f32_e32 v47, v47
	v_exp_f32_e32 v36, v36
	v_exp_f32_e32 v37, v37
	v_exp_f32_e32 v38, v38
	v_exp_f32_e32 v39, v39
	s_mov_b32 s100, 0x18c000
	v_pk_add_f32 v[44:45], v[44:45], 1.0 op_sel_hi:[1,0]
	v_pk_add_f32 v[46:47], v[46:47], 1.0 op_sel_hi:[1,0]
	v_pk_add_f32 v[36:37], v[36:37], 1.0 op_sel_hi:[1,0]
	v_pk_add_f32 v[38:39], v[38:39], 1.0 op_sel_hi:[1,0]
	v_rcp_f32_e32 v44, v44
	v_rcp_f32_e32 v45, v45
	v_rcp_f32_e32 v46, v46
	v_rcp_f32_e32 v47, v47
	v_rcp_f32_e32 v36, v36
	v_rcp_f32_e32 v37, v37
	v_rcp_f32_e32 v38, v38
	v_rcp_f32_e32 v39, v39
	v_lshl_add_u64 v[204:205], v[202:203], 0, s[100:101]
	v_pk_mul_f32 v[44:45], v[228:229], v[44:45] op_sel_hi:[0,1]
	v_pk_mul_f32 v[46:47], v[228:229], v[46:47] op_sel_hi:[0,1]
	v_pk_mul_f32 v[36:37], v[228:229], v[36:37] op_sel_hi:[0,1]
	v_pk_mul_f32 v[38:39], v[228:229], v[38:39] op_sel_hi:[0,1]
	v_pk_mul_f32 v[40:41], v[40:41], v[44:45]
	v_pk_mul_f32 v[42:43], v[42:43], v[46:47]
	v_pk_mul_f32 v[32:33], v[32:33], v[36:37]
	v_pk_mul_f32 v[34:35], v[34:35], v[38:39]
	v_cvt_pk_bf16_f32 v44, v40, v41
	v_cvt_pk_bf16_f32 v45, v42, v43
	v_cvt_pk_bf16_f32 v46, v32, v33
	v_cvt_pk_bf16_f32 v47, v34, v35
	global_store_dwordx4 v[204:205], v[44:47], off nt
	v_pk_mul_f32 v[28:29], v[28:29], v[230:231] op_sel_hi:[1,0]
	v_pk_mul_f32 v[30:31], v[30:31], v[230:231] op_sel_hi:[1,0]
	v_pk_mul_f32 v[20:21], v[20:21], v[230:231] op_sel_hi:[1,0]
	v_pk_mul_f32 v[22:23], v[22:23], v[230:231] op_sel_hi:[1,0]
	v_exp_f32_e32 v28, v28
	v_exp_f32_e32 v29, v29
	v_exp_f32_e32 v30, v30
	v_exp_f32_e32 v31, v31
	v_exp_f32_e32 v20, v20
	v_exp_f32_e32 v21, v21
	v_exp_f32_e32 v22, v22
	v_exp_f32_e32 v23, v23
	s_mov_b32 s100, 0x1b8000
	v_pk_add_f32 v[28:29], v[28:29], 1.0 op_sel_hi:[1,0]
	v_pk_add_f32 v[30:31], v[30:31], 1.0 op_sel_hi:[1,0]
	v_pk_add_f32 v[20:21], v[20:21], 1.0 op_sel_hi:[1,0]
	v_pk_add_f32 v[22:23], v[22:23], 1.0 op_sel_hi:[1,0]
	v_rcp_f32_e32 v28, v28
	v_rcp_f32_e32 v29, v29
	v_rcp_f32_e32 v30, v30
	v_rcp_f32_e32 v31, v31
	v_rcp_f32_e32 v20, v20
	v_rcp_f32_e32 v21, v21
	v_rcp_f32_e32 v22, v22
	v_rcp_f32_e32 v23, v23
	v_lshl_add_u64 v[204:205], v[202:203], 0, s[100:101]
	v_pk_mul_f32 v[28:29], v[232:233], v[28:29] op_sel_hi:[0,1]
	v_pk_mul_f32 v[30:31], v[232:233], v[30:31] op_sel_hi:[0,1]
	v_pk_mul_f32 v[20:21], v[232:233], v[20:21] op_sel_hi:[0,1]
	v_pk_mul_f32 v[22:23], v[232:233], v[22:23] op_sel_hi:[0,1]
	v_pk_mul_f32 v[24:25], v[24:25], v[28:29]
	v_pk_mul_f32 v[26:27], v[26:27], v[30:31]
	v_pk_mul_f32 v[16:17], v[16:17], v[20:21]
	v_pk_mul_f32 v[18:19], v[18:19], v[22:23]
	v_cvt_pk_bf16_f32 v28, v24, v25
	v_cvt_pk_bf16_f32 v29, v26, v27
	v_cvt_pk_bf16_f32 v30, v16, v17
	v_cvt_pk_bf16_f32 v31, v18, v19
	global_store_dwordx4 v[204:205], v[28:31], off nt
	v_pk_mul_f32 v[12:13], v[12:13], v[234:235] op_sel_hi:[1,0]
	v_pk_mul_f32 v[14:15], v[14:15], v[234:235] op_sel_hi:[1,0]
	v_pk_mul_f32 v[4:5], v[4:5], v[234:235] op_sel_hi:[1,0]
	v_pk_mul_f32 v[6:7], v[6:7], v[234:235] op_sel_hi:[1,0]
	v_exp_f32_e32 v12, v12
	v_exp_f32_e32 v13, v13
	v_exp_f32_e32 v14, v14
	v_exp_f32_e32 v15, v15
	v_exp_f32_e32 v4, v4
	v_exp_f32_e32 v5, v5
	v_exp_f32_e32 v6, v6
	v_exp_f32_e32 v7, v7
	s_mov_b32 s100, 0x1e4000
	v_pk_add_f32 v[12:13], v[12:13], 1.0 op_sel_hi:[1,0]
	v_pk_add_f32 v[14:15], v[14:15], 1.0 op_sel_hi:[1,0]
	v_pk_add_f32 v[4:5], v[4:5], 1.0 op_sel_hi:[1,0]
	v_pk_add_f32 v[6:7], v[6:7], 1.0 op_sel_hi:[1,0]
	v_rcp_f32_e32 v12, v12
	v_rcp_f32_e32 v13, v13
	v_rcp_f32_e32 v14, v14
	v_rcp_f32_e32 v15, v15
	v_rcp_f32_e32 v4, v4
	v_rcp_f32_e32 v5, v5
	v_rcp_f32_e32 v6, v6
	v_rcp_f32_e32 v7, v7
	v_lshl_add_u64 v[204:205], v[202:203], 0, s[100:101]
	v_pk_mul_f32 v[12:13], v[236:237], v[12:13] op_sel_hi:[0,1]
	v_pk_mul_f32 v[14:15], v[236:237], v[14:15] op_sel_hi:[0,1]
	v_pk_mul_f32 v[4:5], v[236:237], v[4:5] op_sel_hi:[0,1]
	v_pk_mul_f32 v[6:7], v[236:237], v[6:7] op_sel_hi:[0,1]
	v_pk_mul_f32 v[8:9], v[8:9], v[12:13]
	v_pk_mul_f32 v[10:11], v[10:11], v[14:15]
	v_pk_mul_f32 v[0:1], v[0:1], v[4:5]
	v_pk_mul_f32 v[2:3], v[2:3], v[6:7]
	v_cvt_pk_bf16_f32 v12, v8, v9
	v_cvt_pk_bf16_f32 v13, v10, v11
	v_cvt_pk_bf16_f32 v14, v0, v1
	v_cvt_pk_bf16_f32 v15, v2, v3
	global_store_dwordx4 v[204:205], v[12:15], off nt
	s_movk_i32 s92, 0x37ff
	s_andn2_b64 vcc, exec, s[38:39]
	s_mov_b64 s[22:23], -1
	s_cbranch_vccnz .LBB0_741
	s_andn2_b64 vcc, exec, s[0:1]
	s_cbranch_vccnz .LBB0_740
	s_barrier
	s_branch .LBB0_740
